# grid barrier: the agent-scope invalidate is issued at arrival (the CU issues no L1-allocating loads between arrival and release) and overlaps the arrival round trip / write-back, instead of sitting be
# speedup vs baseline: 1.0103x; 1.0103x over previous
.LBB0_142:
	s_cmp_lt_i32 s89, 3
	s_cbranch_scc1 .LBB0_188
	s_waitcnt vmcnt(0) lgkmcnt(0)
	s_barrier
	v_readlane_b32 s0, v254, 0
	v_readlane_b32 s4, v254, 6
	v_readlane_b32 s5, v254, 5
	s_andn2_b32 s0, s0, 63
	s_cmp_lg_u32 s0, 0
	s_cbranch_scc1 .Lnb_end_1
	s_mov_b64 s[2:3], exec
	s_mov_b64 exec, 1
	v_mov_b32_e32 v0, s4
	v_mov_b32_e32 v4, 1
	v_mov_b32_e32 v5, 0
	ds_read_b64 v[2:3], v0
	s_lshl_b32 s6, s5, 8
	s_add_u32 s8, s84, s6
	s_addc_u32 s9, s85, 0
	s_add_u32 s16, s8, 0x2400
	s_addc_u32 s17, s9, 0
	s_add_u32 s8, s8, 0x1400
	s_addc_u32 s9, s9, 0
	s_add_u32 s20, s84, 0x3400
	s_addc_u32 s21, s85, 0
	s_add_u32 s26, s84, 0x2400
	s_addc_u32 s27, s85, 0
	s_mov_b32 s24, 0
	global_atomic_add v6, v5, v4, s[8:9] sc0
	buffer_inv sc1
	s_add_u32 s13, s98, 1
	s_waitcnt vmcnt(1) lgkmcnt(0)
	v_readfirstlane_b32 s10, v6
	v_readfirstlane_b32 s11, v2
	v_readfirstlane_b32 s12, v3
	s_add_u32 s10, s10, 1
	s_mul_i32 s14, s13, s11
	s_cmp_eq_u32 s10, s14
	s_cbranch_scc1 .Lnb_leader_1

.Lnb_acq_1:
	s_waitcnt vmcnt(0)
	s_mov_b64 exec, s[2:3]

.LBB0_512:
	s_cmp_lt_i32 s89, 4
	s_cbranch_scc1 .LBB0_558
	s_waitcnt vmcnt(0) lgkmcnt(0)
	s_barrier
	v_readlane_b32 s0, v254, 0
	v_readlane_b32 s4, v254, 6
	v_readlane_b32 s5, v254, 5
	s_andn2_b32 s0, s0, 63
	s_cmp_lg_u32 s0, 0
	s_cbranch_scc1 .Lnb_end_2
	s_mov_b64 s[2:3], exec
	s_mov_b64 exec, 1
	v_mov_b32_e32 v0, s4
	v_mov_b32_e32 v4, 1
	v_mov_b32_e32 v5, 0
	ds_read_b64 v[2:3], v0
	s_lshl_b32 s6, s5, 8
	s_add_u32 s8, s84, s6
	s_addc_u32 s9, s85, 0
	s_add_u32 s16, s8, 0x2400
	s_addc_u32 s17, s9, 0
	s_add_u32 s8, s8, 0x1400
	s_addc_u32 s9, s9, 0
	s_add_u32 s20, s84, 0x3400
	s_addc_u32 s21, s85, 0
	s_add_u32 s26, s84, 0x2400
	s_addc_u32 s27, s85, 0
	s_mov_b32 s24, 0
	global_atomic_add v6, v5, v4, s[8:9] sc0
	buffer_inv sc1
	s_add_u32 s13, s98, 1
	s_waitcnt vmcnt(1) lgkmcnt(0)
	v_readfirstlane_b32 s10, v6
	v_readfirstlane_b32 s11, v2
	v_readfirstlane_b32 s12, v3
	s_add_u32 s10, s10, 1
	s_mul_i32 s14, s13, s11
	s_cmp_eq_u32 s10, s14
	s_cbranch_scc1 .Lnb_leader_2

.LBB0_857:
	s_cmp_lt_i32 s89, 5
	s_barrier
	s_cbranch_scc1 .LBB0_906
	s_waitcnt vmcnt(0) lgkmcnt(0)
	s_barrier
	v_readlane_b32 s0, v254, 0
	v_readlane_b32 s4, v254, 6
	v_readlane_b32 s5, v254, 5
	s_andn2_b32 s0, s0, 63
	s_cmp_lg_u32 s0, 0
	s_cbranch_scc1 .Lnb_end_3
	s_mov_b64 s[2:3], exec
	s_mov_b64 exec, 1
	v_mov_b32_e32 v0, s4
	v_mov_b32_e32 v4, 1
	v_mov_b32_e32 v5, 0
	ds_read_b64 v[2:3], v0
	s_lshl_b32 s6, s5, 8
	s_add_u32 s8, s84, s6
	s_addc_u32 s9, s85, 0
	s_add_u32 s16, s8, 0x2400
	s_addc_u32 s17, s9, 0
	s_add_u32 s8, s8, 0x1400
	s_addc_u32 s9, s9, 0
	s_add_u32 s20, s84, 0x3400
	s_addc_u32 s21, s85, 0
	s_add_u32 s26, s84, 0x2400
	s_addc_u32 s27, s85, 0
	s_mov_b32 s24, 0
	global_atomic_add v6, v5, v4, s[8:9] sc0
	buffer_inv sc1
	s_add_u32 s13, s98, 1
	s_waitcnt vmcnt(1) lgkmcnt(0)
	v_readfirstlane_b32 s10, v6
	v_readfirstlane_b32 s11, v2
	v_readfirstlane_b32 s12, v3
	s_add_u32 s10, s10, 1
	s_mul_i32 s14, s13, s11
	s_cmp_eq_u32 s10, s14
	s_cbranch_scc1 .Lnb_leader_3

.LBB0_933:
	s_cmp_lt_i32 s89, 6
	s_cbranch_scc1 .LBB0_979
	s_waitcnt vmcnt(0) lgkmcnt(0)
	s_barrier
	v_readlane_b32 s0, v254, 0
	v_readlane_b32 s4, v254, 6
	v_readlane_b32 s5, v254, 5
	s_andn2_b32 s0, s0, 63
	s_cmp_lg_u32 s0, 0
	s_cbranch_scc1 .Lnb_end_4
	s_mov_b64 s[2:3], exec
	s_mov_b64 exec, 1
	v_mov_b32_e32 v0, s4
	v_mov_b32_e32 v4, 1
	v_mov_b32_e32 v5, 0
	ds_read_b64 v[2:3], v0
	s_lshl_b32 s6, s5, 8
	s_add_u32 s8, s84, s6
	s_addc_u32 s9, s85, 0
	s_add_u32 s16, s8, 0x2400
	s_addc_u32 s17, s9, 0
	s_add_u32 s8, s8, 0x1400
	s_addc_u32 s9, s9, 0
	s_add_u32 s20, s84, 0x3400
	s_addc_u32 s21, s85, 0
	s_add_u32 s26, s84, 0x2400
	s_addc_u32 s27, s85, 0
	s_mov_b32 s24, 0
	global_atomic_add v6, v5, v4, s[8:9] sc0
	buffer_inv sc1
	s_add_u32 s13, s98, 1
	s_waitcnt vmcnt(1) lgkmcnt(0)
	v_readfirstlane_b32 s10, v6
	v_readfirstlane_b32 s11, v2
	v_readfirstlane_b32 s12, v3
	s_add_u32 s10, s10, 1
	s_mul_i32 s14, s13, s11
	s_cmp_eq_u32 s10, s14
	s_cbranch_scc1 .Lnb_leader_4

.LBB0_1175:
	s_cmp_lt_i32 s89, 7
	s_cbranch_scc1 .LBB0_1221
	s_waitcnt vmcnt(0) lgkmcnt(0)
	s_barrier
	v_readlane_b32 s0, v254, 0
	v_readlane_b32 s4, v254, 6
	v_readlane_b32 s5, v254, 5
	s_andn2_b32 s0, s0, 63
	s_cmp_lg_u32 s0, 0
	s_cbranch_scc1 .Lnb_end_5
	s_mov_b64 s[2:3], exec
	s_mov_b64 exec, 1
	v_mov_b32_e32 v0, s4
	v_mov_b32_e32 v4, 1
	v_mov_b32_e32 v5, 0
	ds_read_b64 v[2:3], v0
	s_lshl_b32 s6, s5, 8
	s_add_u32 s8, s84, s6
	s_addc_u32 s9, s85, 0
	s_add_u32 s16, s8, 0x2400
	s_addc_u32 s17, s9, 0
	s_add_u32 s8, s8, 0x1400
	s_addc_u32 s9, s9, 0
	s_add_u32 s20, s84, 0x3400
	s_addc_u32 s21, s85, 0
	s_add_u32 s26, s84, 0x2400
	s_addc_u32 s27, s85, 0
	s_mov_b32 s24, 0
	global_atomic_add v6, v5, v4, s[8:9] sc0
	buffer_inv sc1
	s_add_u32 s13, s98, 1
	s_waitcnt vmcnt(1) lgkmcnt(0)
	v_readfirstlane_b32 s10, v6
	v_readfirstlane_b32 s11, v2
	v_readfirstlane_b32 s12, v3
	s_add_u32 s10, s10, 1
	s_mul_i32 s14, s13, s11
	s_cmp_eq_u32 s10, s14
	s_cbranch_scc1 .Lnb_leader_5

.LBB0_1237:
	s_cmp_lt_i32 s89, 8
	s_barrier
	s_cbranch_scc1 .LBB0_1283
	s_waitcnt vmcnt(0) lgkmcnt(0)
	s_barrier
	v_readlane_b32 s0, v254, 0
	v_readlane_b32 s4, v254, 6
	v_readlane_b32 s5, v254, 5
	s_andn2_b32 s0, s0, 63
	s_cmp_lg_u32 s0, 0
	s_cbranch_scc1 .Lnb_end_6
	s_mov_b64 s[2:3], exec
	s_mov_b64 exec, 1
	v_mov_b32_e32 v0, s4
	v_mov_b32_e32 v4, 1
	v_mov_b32_e32 v5, 0
	ds_read_b64 v[2:3], v0
	s_lshl_b32 s6, s5, 8
	s_add_u32 s8, s84, s6
	s_addc_u32 s9, s85, 0
	s_add_u32 s16, s8, 0x2400
	s_addc_u32 s17, s9, 0
	s_add_u32 s8, s8, 0x1400
	s_addc_u32 s9, s9, 0
	s_add_u32 s20, s84, 0x3400
	s_addc_u32 s21, s85, 0
	s_add_u32 s26, s84, 0x2400
	s_addc_u32 s27, s85, 0
	s_mov_b32 s24, 0
	global_atomic_add v6, v5, v4, s[8:9] sc0
	buffer_inv sc1
	s_add_u32 s13, s98, 1
	s_waitcnt vmcnt(1) lgkmcnt(0)
	v_readfirstlane_b32 s10, v6
	v_readfirstlane_b32 s11, v2
	v_readfirstlane_b32 s12, v3
	s_add_u32 s10, s10, 1
	s_mul_i32 s14, s13, s11
	s_cmp_eq_u32 s10, s14
	s_cbranch_scc1 .Lnb_leader_6

.LBB0_1308:
	s_cmp_lt_i32 s89, 9
	s_cbranch_scc1 .LBB0_1354
	s_waitcnt vmcnt(0) lgkmcnt(0)
	s_barrier
	v_readlane_b32 s0, v254, 0
	v_readlane_b32 s4, v254, 6
	v_readlane_b32 s5, v254, 5
	s_andn2_b32 s0, s0, 63
	s_cmp_lg_u32 s0, 0
	s_cbranch_scc1 .Lnb_end_7
	s_mov_b64 s[2:3], exec
	s_mov_b64 exec, 1
	v_mov_b32_e32 v0, s4
	v_mov_b32_e32 v4, 1
	v_mov_b32_e32 v5, 0
	ds_read_b64 v[2:3], v0
	s_lshl_b32 s6, s5, 8
	s_add_u32 s8, s84, s6
	s_addc_u32 s9, s85, 0
	s_add_u32 s16, s8, 0x2400
	s_addc_u32 s17, s9, 0
	s_add_u32 s8, s8, 0x1400
	s_addc_u32 s9, s9, 0
	s_add_u32 s20, s84, 0x3400
	s_addc_u32 s21, s85, 0
	s_add_u32 s26, s84, 0x2400
	s_addc_u32 s27, s85, 0
	s_mov_b32 s24, 0
	global_atomic_add v6, v5, v4, s[8:9] sc0
	buffer_inv sc1
	s_add_u32 s13, s98, 1
	s_waitcnt vmcnt(1) lgkmcnt(0)
	v_readfirstlane_b32 s10, v6
	v_readfirstlane_b32 s11, v2
	v_readfirstlane_b32 s12, v3
	s_add_u32 s10, s10, 1
	s_mul_i32 s14, s13, s11
	s_cmp_eq_u32 s10, s14
	s_cbranch_scc1 .Lnb_leader_7

.LBB0_1481:
	s_cmp_lt_i32 s89, 10
	s_cbranch_scc1 .LBB0_1527
	s_waitcnt vmcnt(0) lgkmcnt(0)
	s_barrier
	v_readlane_b32 s0, v254, 0
	v_readlane_b32 s4, v254, 6
	v_readlane_b32 s5, v254, 5
	s_andn2_b32 s0, s0, 63
	s_cmp_lg_u32 s0, 0
	s_cbranch_scc1 .Lnb_end_8
	s_mov_b64 s[2:3], exec
	s_mov_b64 exec, 1
	v_mov_b32_e32 v0, s4
	v_mov_b32_e32 v4, 1
	v_mov_b32_e32 v5, 0
	ds_read_b64 v[2:3], v0
	s_lshl_b32 s6, s5, 8
	s_add_u32 s8, s84, s6
	s_addc_u32 s9, s85, 0
	s_add_u32 s16, s8, 0x2400
	s_addc_u32 s17, s9, 0
	s_add_u32 s8, s8, 0x1400
	s_addc_u32 s9, s9, 0
	s_add_u32 s20, s84, 0x3400
	s_addc_u32 s21, s85, 0
	s_add_u32 s26, s84, 0x2400
	s_addc_u32 s27, s85, 0
	s_mov_b32 s24, 0
	global_atomic_add v6, v5, v4, s[8:9] sc0
	buffer_inv sc1
	s_add_u32 s13, s98, 1
	s_waitcnt vmcnt(1) lgkmcnt(0)
	v_readfirstlane_b32 s10, v6
	v_readfirstlane_b32 s11, v2
	v_readfirstlane_b32 s12, v3
	s_add_u32 s10, s10, 1
	s_mul_i32 s14, s13, s11
	s_cmp_eq_u32 s10, s14
	s_cbranch_scc1 .Lnb_leader_8

.LBB0_1563:
	s_cmp_lt_i32 s89, 11
	s_barrier
	s_cbranch_scc1 .LBB0_1609
	s_waitcnt vmcnt(0) lgkmcnt(0)
	s_barrier
	v_readlane_b32 s0, v254, 0
	v_readlane_b32 s4, v254, 6
	v_readlane_b32 s5, v254, 5
	s_andn2_b32 s0, s0, 63
	s_cmp_lg_u32 s0, 0
	s_cbranch_scc1 .Lnb_end_9
	s_mov_b64 s[2:3], exec
	s_mov_b64 exec, 1
	v_mov_b32_e32 v0, s4
	v_mov_b32_e32 v4, 1
	v_mov_b32_e32 v5, 0
	ds_read_b64 v[2:3], v0
	s_lshl_b32 s6, s5, 8
	s_add_u32 s8, s84, s6
	s_addc_u32 s9, s85, 0
	s_add_u32 s16, s8, 0x2400
	s_addc_u32 s17, s9, 0
	s_add_u32 s8, s8, 0x1400
	s_addc_u32 s9, s9, 0
	s_add_u32 s20, s84, 0x3400
	s_addc_u32 s21, s85, 0
	s_add_u32 s26, s84, 0x2400
	s_addc_u32 s27, s85, 0
	s_mov_b32 s24, 0
	global_atomic_add v6, v5, v4, s[8:9] sc0
	buffer_inv sc1
	s_add_u32 s13, s98, 1
	s_waitcnt vmcnt(1) lgkmcnt(0)
	v_readfirstlane_b32 s10, v6
	v_readfirstlane_b32 s11, v2
	v_readfirstlane_b32 s12, v3
	s_add_u32 s10, s10, 1
	s_mul_i32 s14, s13, s11
	s_cmp_eq_u32 s10, s14
	s_cbranch_scc1 .Lnb_leader_9

.LBB0_1651:
	s_cmp_lt_i32 s89, 12
	s_cbranch_scc1 .LBB0_1697
	s_waitcnt vmcnt(0) lgkmcnt(0)
	s_barrier
	v_readlane_b32 s0, v254, 0
	v_readlane_b32 s4, v254, 6
	v_readlane_b32 s5, v254, 5
	s_andn2_b32 s0, s0, 63
	s_cmp_lg_u32 s0, 0
	s_cbranch_scc1 .Lnb_end_10
	s_mov_b64 s[2:3], exec
	s_mov_b64 exec, 1
	v_mov_b32_e32 v0, s4
	v_mov_b32_e32 v4, 1
	v_mov_b32_e32 v5, 0
	ds_read_b64 v[2:3], v0
	s_lshl_b32 s6, s5, 8
	s_add_u32 s8, s84, s6
	s_addc_u32 s9, s85, 0
	s_add_u32 s16, s8, 0x2400
	s_addc_u32 s17, s9, 0
	s_add_u32 s8, s8, 0x1400
	s_addc_u32 s9, s9, 0
	s_add_u32 s20, s84, 0x3400
	s_addc_u32 s21, s85, 0
	s_add_u32 s26, s84, 0x2400
	s_addc_u32 s27, s85, 0
	s_mov_b32 s24, 0
	global_atomic_add v6, v5, v4, s[8:9] sc0
	buffer_inv sc1
	s_add_u32 s13, s98, 1
	s_waitcnt vmcnt(1) lgkmcnt(0)
	v_readfirstlane_b32 s10, v6
	v_readfirstlane_b32 s11, v2
	v_readfirstlane_b32 s12, v3
	s_add_u32 s10, s10, 1
	s_mul_i32 s14, s13, s11
	s_cmp_eq_u32 s10, s14
	s_cbranch_scc1 .Lnb_leader_10

.LBB0_2021:
	s_cmp_lt_i32 s89, 13
	s_cbranch_scc1 .LBB0_2067
	s_waitcnt vmcnt(0) lgkmcnt(0)
	s_barrier
	v_readlane_b32 s0, v254, 0
	v_readlane_b32 s4, v254, 6
	v_readlane_b32 s5, v254, 5
	s_andn2_b32 s0, s0, 63
	s_cmp_lg_u32 s0, 0
	s_cbranch_scc1 .Lnb_end_11
	s_mov_b64 s[2:3], exec
	s_mov_b64 exec, 1
	v_mov_b32_e32 v0, s4
	v_mov_b32_e32 v4, 1
	v_mov_b32_e32 v5, 0
	ds_read_b64 v[2:3], v0
	s_lshl_b32 s6, s5, 8
	s_add_u32 s8, s84, s6
	s_addc_u32 s9, s85, 0
	s_add_u32 s16, s8, 0x2400
	s_addc_u32 s17, s9, 0
	s_add_u32 s8, s8, 0x1400
	s_addc_u32 s9, s9, 0
	s_add_u32 s20, s84, 0x3400
	s_addc_u32 s21, s85, 0
	s_add_u32 s26, s84, 0x2400
	s_addc_u32 s27, s85, 0
	s_mov_b32 s24, 0
	global_atomic_add v6, v5, v4, s[8:9] sc0
	buffer_inv sc1
	s_add_u32 s13, s98, 1
	s_waitcnt vmcnt(1) lgkmcnt(0)
	v_readfirstlane_b32 s10, v6
	v_readfirstlane_b32 s11, v2
	v_readfirstlane_b32 s12, v3
	s_add_u32 s10, s10, 1
	s_mul_i32 s14, s13, s11
	s_cmp_eq_u32 s10, s14
	s_cbranch_scc1 .Lnb_leader_11

.LBB0_2366:
	s_cmp_lt_i32 s89, 14
	s_barrier
	s_cbranch_scc1 .LBB0_2415
	s_waitcnt vmcnt(0) lgkmcnt(0)
	s_barrier
	v_readlane_b32 s0, v254, 0
	v_readlane_b32 s4, v254, 6
	v_readlane_b32 s5, v254, 5
	s_andn2_b32 s0, s0, 63
	s_cmp_lg_u32 s0, 0
	s_cbranch_scc1 .Lnb_end_12
	s_mov_b64 s[2:3], exec
	s_mov_b64 exec, 1
	v_mov_b32_e32 v0, s4
	v_mov_b32_e32 v4, 1
	v_mov_b32_e32 v5, 0
	ds_read_b64 v[2:3], v0
	s_lshl_b32 s6, s5, 8
	s_add_u32 s8, s84, s6
	s_addc_u32 s9, s85, 0
	s_add_u32 s16, s8, 0x2400
	s_addc_u32 s17, s9, 0
	s_add_u32 s8, s8, 0x1400
	s_addc_u32 s9, s9, 0
	s_add_u32 s20, s84, 0x3400
	s_addc_u32 s21, s85, 0
	s_add_u32 s26, s84, 0x2400
	s_addc_u32 s27, s85, 0
	s_mov_b32 s24, 0
	global_atomic_add v6, v5, v4, s[8:9] sc0
	buffer_inv sc1
	s_add_u32 s13, s98, 1
	s_waitcnt vmcnt(1) lgkmcnt(0)
	v_readfirstlane_b32 s10, v6
	v_readfirstlane_b32 s11, v2
	v_readfirstlane_b32 s12, v3
	s_add_u32 s10, s10, 1
	s_mul_i32 s14, s13, s11
	s_cmp_eq_u32 s10, s14
	s_cbranch_scc1 .Lnb_leader_12

.LBB0_2442:
	s_cmp_lt_i32 s89, 15
	s_cbranch_scc1 .LBB0_2488
	s_waitcnt vmcnt(0) lgkmcnt(0)
	s_barrier
	v_readlane_b32 s0, v254, 0
	v_readlane_b32 s4, v254, 6
	v_readlane_b32 s5, v254, 5
	s_andn2_b32 s0, s0, 63
	s_cmp_lg_u32 s0, 0
	s_cbranch_scc1 .Lnb_end_13
	s_mov_b64 s[2:3], exec
	s_mov_b64 exec, 1
	v_mov_b32_e32 v0, s4
	v_mov_b32_e32 v4, 1
	v_mov_b32_e32 v5, 0
	ds_read_b64 v[2:3], v0
	s_lshl_b32 s6, s5, 8
	s_add_u32 s8, s84, s6
	s_addc_u32 s9, s85, 0
	s_add_u32 s16, s8, 0x2400
	s_addc_u32 s17, s9, 0
	s_add_u32 s8, s8, 0x1400
	s_addc_u32 s9, s9, 0
	s_add_u32 s20, s84, 0x3400
	s_addc_u32 s21, s85, 0
	s_add_u32 s26, s84, 0x2400
	s_addc_u32 s27, s85, 0
	s_mov_b32 s24, 0
	global_atomic_add v6, v5, v4, s[8:9] sc0
	buffer_inv sc1
	s_add_u32 s13, s98, 1
	s_waitcnt vmcnt(1) lgkmcnt(0)
	v_readfirstlane_b32 s10, v6
	v_readfirstlane_b32 s11, v2
	v_readfirstlane_b32 s12, v3
	s_add_u32 s10, s10, 1
	s_mul_i32 s14, s13, s11
	s_cmp_eq_u32 s10, s14
	s_cbranch_scc1 .Lnb_leader_13

.LBB0_2611:
	s_cmp_lt_i32 s89, 16
	s_cbranch_scc1 .LBB0_2657
	s_waitcnt vmcnt(0) lgkmcnt(0)
	s_barrier
	v_readlane_b32 s0, v254, 0
	v_readlane_b32 s4, v254, 6
	v_readlane_b32 s5, v254, 5
	s_andn2_b32 s0, s0, 63
	s_cmp_lg_u32 s0, 0
	s_cbranch_scc1 .Lnb_end_14
	s_mov_b64 s[2:3], exec
	s_mov_b64 exec, 1
	v_mov_b32_e32 v0, s4
	v_mov_b32_e32 v4, 1
	v_mov_b32_e32 v5, 0
	ds_read_b64 v[2:3], v0
	s_lshl_b32 s6, s5, 8
	s_add_u32 s8, s84, s6
	s_addc_u32 s9, s85, 0
	s_add_u32 s16, s8, 0x2400
	s_addc_u32 s17, s9, 0
	s_add_u32 s8, s8, 0x1400
	s_addc_u32 s9, s9, 0
	s_add_u32 s20, s84, 0x3400
	s_addc_u32 s21, s85, 0
	s_add_u32 s26, s84, 0x2400
	s_addc_u32 s27, s85, 0
	s_mov_b32 s24, 0
	global_atomic_add v6, v5, v4, s[8:9] sc0
	buffer_inv sc1
	s_add_u32 s13, s98, 1
	s_waitcnt vmcnt(1) lgkmcnt(0)
	v_readfirstlane_b32 s10, v6
	v_readfirstlane_b32 s11, v2
	v_readfirstlane_b32 s12, v3
	s_add_u32 s10, s10, 1
	s_mul_i32 s14, s13, s11
	s_cmp_eq_u32 s10, s14
	s_cbranch_scc1 .Lnb_leader_14

.LBB0_2665:
	s_cmp_lt_i32 s89, 17
	s_barrier
	s_cbranch_scc1 .LBB0_2711
	s_waitcnt vmcnt(0) lgkmcnt(0)
	s_barrier
	v_readlane_b32 s0, v254, 0
	v_readlane_b32 s4, v254, 6
	v_readlane_b32 s5, v254, 5
	s_andn2_b32 s0, s0, 63
	s_cmp_lg_u32 s0, 0
	s_cbranch_scc1 .Lnb_end_15
	s_mov_b64 s[2:3], exec
	s_mov_b64 exec, 1
	v_mov_b32_e32 v0, s4
	v_mov_b32_e32 v4, 1
	v_mov_b32_e32 v5, 0
	ds_read_b64 v[2:3], v0
	s_lshl_b32 s6, s5, 8
	s_add_u32 s8, s84, s6
	s_addc_u32 s9, s85, 0
	s_add_u32 s16, s8, 0x2400
	s_addc_u32 s17, s9, 0
	s_add_u32 s8, s8, 0x1400
	s_addc_u32 s9, s9, 0
	s_add_u32 s20, s84, 0x3400
	s_addc_u32 s21, s85, 0
	s_add_u32 s26, s84, 0x2400
	s_addc_u32 s27, s85, 0
	s_mov_b32 s24, 0
	global_atomic_add v6, v5, v4, s[8:9] sc0
	buffer_inv sc1
	s_add_u32 s13, s98, 1
	s_waitcnt vmcnt(1) lgkmcnt(0)
	v_readfirstlane_b32 s10, v6
	v_readfirstlane_b32 s11, v2
	v_readfirstlane_b32 s12, v3
	s_add_u32 s10, s10, 1
	s_mul_i32 s14, s13, s11
	s_cmp_eq_u32 s10, s14
	s_cbranch_scc1 .Lnb_leader_15

.LBB0_2736:
	s_cmp_lt_i32 s89, 18
	s_cbranch_scc1 .LBB0_2782
	s_waitcnt vmcnt(0) lgkmcnt(0)
	s_barrier
	v_readlane_b32 s0, v254, 0
	v_readlane_b32 s4, v254, 6
	v_readlane_b32 s5, v254, 5
	s_andn2_b32 s0, s0, 63
	s_cmp_lg_u32 s0, 0
	s_cbranch_scc1 .Lnb_end_16
	s_mov_b64 s[2:3], exec
	s_mov_b64 exec, 1
	v_mov_b32_e32 v0, s4
	v_mov_b32_e32 v4, 1
	v_mov_b32_e32 v5, 0
	ds_read_b64 v[2:3], v0
	s_lshl_b32 s6, s5, 8
	s_add_u32 s8, s84, s6
	s_addc_u32 s9, s85, 0
	s_add_u32 s16, s8, 0x2400
	s_addc_u32 s17, s9, 0
	s_add_u32 s8, s8, 0x1400
	s_addc_u32 s9, s9, 0
	s_add_u32 s20, s84, 0x3400
	s_addc_u32 s21, s85, 0
	s_add_u32 s26, s84, 0x2400
	s_addc_u32 s27, s85, 0
	s_mov_b32 s24, 0
	global_atomic_add v6, v5, v4, s[8:9] sc0
	buffer_inv sc1
	s_add_u32 s13, s98, 1
	s_waitcnt vmcnt(1) lgkmcnt(0)
	v_readfirstlane_b32 s10, v6
	v_readfirstlane_b32 s11, v2
	v_readfirstlane_b32 s12, v3
	s_add_u32 s10, s10, 1
	s_mul_i32 s14, s13, s11
	s_cmp_eq_u32 s10, s14
	s_cbranch_scc1 .Lnb_leader_16

.LBB0_2918:
	s_cmp_lt_i32 s89, 19
	s_cbranch_scc1 .LBB0_2980
	s_waitcnt vmcnt(0) lgkmcnt(0)
	s_barrier
	v_readlane_b32 s0, v254, 0
	v_readlane_b32 s4, v254, 6
	v_readlane_b32 s5, v254, 5
	s_andn2_b32 s0, s0, 63
	s_cmp_lg_u32 s0, 0
	s_cbranch_scc1 .Lnb_end_17
	s_mov_b64 s[2:3], exec
	s_mov_b64 exec, 1
	v_mov_b32_e32 v0, s4
	v_mov_b32_e32 v4, 1
	v_mov_b32_e32 v5, 0
	ds_read_b64 v[2:3], v0
	s_lshl_b32 s6, s5, 8
	s_add_u32 s8, s84, s6
	s_addc_u32 s9, s85, 0
	s_add_u32 s16, s8, 0x2400
	s_addc_u32 s17, s9, 0
	s_add_u32 s8, s8, 0x1400
	s_addc_u32 s9, s9, 0
	s_add_u32 s20, s84, 0x3400
	s_addc_u32 s21, s85, 0
	s_add_u32 s26, s84, 0x2400
	s_addc_u32 s27, s85, 0
	s_mov_b32 s24, 0
	global_atomic_add v6, v5, v4, s[8:9] sc0
	buffer_inv sc1
	s_add_u32 s13, s98, 1
	s_waitcnt vmcnt(1) lgkmcnt(0)
	v_readfirstlane_b32 s10, v6
	v_readfirstlane_b32 s11, v2
	v_readfirstlane_b32 s12, v3
	s_add_u32 s10, s10, 1
	s_mul_i32 s14, s13, s11
	s_cmp_eq_u32 s10, s14
	s_cbranch_scc1 .Lnb_leader_17
